# MLA loop: QK accumulator chains run back to back (q2 fragments re-read) for deeper LDS prefetch
# speedup vs baseline: 1.0034x; 1.0034x over previous
.LBB0_762:
	ds_read_b128 v[64:67], v189 offset:49152
	ds_read_b128 v[236:239], v191 offset:49152
	ds_read_b128 v[240:243], v193 offset:49152
	ds_read_b128 v[244:247], v195 offset:49152
	ds_read_b128 v[248:251], v196 offset:49152
	s_add_i32 s9, s24, -1
	s_cmp_lt_u32 s9, 3
	s_cselect_b32 s100, s46, s68
	s_add_i32 s100, s100, s8
	s_ashr_i32 s101, s100, 31
	s_add_i32 s0, 0, 0x12800
	s_waitcnt lgkmcnt(4)
	v_mfma_f32_32x32x16_bf16 v[80:95], v[64:67], v[124:127], 0
	v_exp_f32_e32 v140, v140
	v_exp_f32_e32 v141, v141
	v_add_u32_e32 v211, s0, v198
	s_waitcnt lgkmcnt(3)
	v_mfma_f32_32x32x16_bf16 v[80:95], v[236:239], v[120:123], v[80:95]
	ds_read_b128 v[236:239], v194 offset:49152
	v_exp_f32_e32 v138, v138
	v_exp_f32_e32 v139, v139
	v_add_u32_e32 v210, s0, v200
	s_waitcnt lgkmcnt(3)
	v_mfma_f32_32x32x16_bf16 v[80:95], v[240:243], v[116:119], v[80:95]
	ds_read_b128 v[240:243], v192 offset:49152
	v_exp_f32_e32 v214, v130
	v_exp_f32_e32 v215, v131
	v_add_u32_e32 v216, s0, v202
	s_waitcnt lgkmcnt(3)
	v_mfma_f32_32x32x16_bf16 v[80:95], v[244:247], v[112:115], v[80:95]
	ds_read_b128 v[244:247], v190 offset:49152
	v_exp_f32_e32 v142, v142
	v_exp_f32_e32 v143, v143
	v_add_u32_e32 v217, s0, v204
	s_waitcnt lgkmcnt(3)
	v_mfma_f32_32x32x16_bf16 v[80:95], v[248:251], v[108:111], v[80:95]
	ds_read_b128 v[248:251], v211
	v_exp_f32_e32 v136, v136
	v_exp_f32_e32 v137, v137
	v_cvt_pk_bf16_f32 v130, v156, v158
	s_waitcnt lgkmcnt(3)
	v_mfma_f32_32x32x16_bf16 v[80:95], v[236:239], v[104:107], v[80:95]
	ds_read_b128 v[236:239], v182
	v_exp_f32_e32 v212, v132
	v_exp_f32_e32 v213, v133
	v_cvt_pk_bf16_f32 v131, v154, v155
	s_waitcnt lgkmcnt(3)
	v_mfma_f32_32x32x16_bf16 v[80:95], v[240:243], v[100:103], v[80:95]
	ds_read_b128 v[240:243], v210
	v_exp_f32_e32 v220, v128
	v_add_f32_e32 v128, 0, v159
	v_add_f32_e32 v128, v161, v128
	v_add_f32_e32 v128, v157, v128
	s_waitcnt lgkmcnt(3)
	v_mfma_f32_32x32x16_bf16 v[80:95], v[244:247], v[96:99], v[80:95]
	ds_read_b128 v[244:247], v182 offset:1024
	v_add_f32_e32 v128, v160, v128
	v_add_f32_e32 v128, v156, v128
	v_add_f32_e32 v128, v158, v128
	v_add_f32_e32 v128, v154, v128
	v_add_f32_e32 v128, v155, v128
	s_waitcnt lgkmcnt(2)
	v_mfma_f32_32x32x16_bf16 v[80:95], v[248:251], v[236:239], v[80:95]
	ds_read_b128 v[248:251], v216
	ds_read_b128 v[236:239], v182 offset:2048
	v_add_f32_e32 v128, v151, v128
	v_add_f32_e32 v128, v153, v128
	v_add_f32_e32 v128, v150, v128
	v_add_f32_e32 v128, v152, v128
	v_add_f32_e32 v128, v147, v128
	s_waitcnt lgkmcnt(2)
	v_mfma_f32_32x32x16_bf16 v[80:95], v[240:243], v[244:247], v[80:95]
	ds_read_b128 v[240:243], v217
	ds_read_b128 v[244:247], v182 offset:3072
	ds_read_b128 v[68:71], v189 offset:57344
	v_add_f32_e32 v128, v149, v128
	v_add_f32_e32 v128, v146, v128
	v_add_f32_e32 v128, v148, v128
	v_add_f32_e32 v128, v140, v128
	v_add_f32_e32 v128, v141, v128
	s_waitcnt lgkmcnt(3)
	v_mfma_f32_32x32x16_bf16 v[80:95], v[248:251], v[236:239], v[80:95]
	ds_read_b128 v[248:251], v191 offset:57344
	ds_read_b128 v[236:239], v193 offset:57344
	v_add_f32_e32 v128, v138, v128
	v_add_f32_e32 v128, v139, v128
	v_add_f32_e32 v128, v212, v128
	v_exp_f32_e32 v221, v129
	s_waitcnt lgkmcnt(3)
	v_mfma_f32_32x32x16_bf16 v[80:95], v[240:243], v[244:247], v[80:95]
	ds_read_b128 v[240:243], v195 offset:57344
	ds_read_b128 v[244:247], v196 offset:57344
	v_add_f32_e32 v128, v213, v128
	v_add_f32_e32 v128, v214, v128
	v_add_f32_e32 v128, v215, v128
	v_add_f32_e32 v128, v220, v128
	v_add_f32_e32 v128, v221, v128
	s_waitcnt lgkmcnt(4)
	v_mfma_f32_32x32x16_bf16 v[64:79], v[68:71], v[124:127], 0
	v_exp_f32_e32 v223, v134
	v_add_f32_e32 v128, v142, v128
	v_exp_f32_e32 v224, v135
	s_waitcnt lgkmcnt(3)
	v_mfma_f32_32x32x16_bf16 v[64:79], v[248:251], v[120:123], v[64:79]
	ds_read_b128 v[248:251], v194 offset:57344
	v_add_f32_e32 v128, v143, v128
	v_add_f32_e32 v128, v136, v128
	v_add_f32_e32 v128, v137, v128
	v_add_f32_e32 v128, v223, v128
	v_add_f32_e32 v218, v224, v128
	s_waitcnt lgkmcnt(3)
	v_mfma_f32_32x32x16_bf16 v[64:79], v[236:239], v[116:119], v[64:79]
	ds_read_b128 v[236:239], v192 offset:57344
	v_mov_b32_e32 v219, v218
	v_cvt_pk_bf16_f32 v128, v159, v161
	v_cvt_pk_bf16_f32 v129, v157, v160
	v_cvt_pk_bf16_f32 v132, v151, v153
	v_cvt_pk_bf16_f32 v133, v150, v152
	s_waitcnt lgkmcnt(3)
	v_mfma_f32_32x32x16_bf16 v[64:79], v[240:243], v[112:115], v[64:79]
	ds_read_b128 v[240:243], v190 offset:57344
	v_cvt_pk_bf16_f32 v134, v147, v149
	v_cvt_pk_bf16_f32 v135, v146, v148
	v_cvt_pk_bf16_f32 v154, v140, v141
	v_cvt_pk_bf16_f32 v155, v138, v139
	v_cvt_pk_bf16_f32 v156, v212, v213
	s_waitcnt lgkmcnt(3)
	v_mfma_f32_32x32x16_bf16 v[64:79], v[244:247], v[108:111], v[64:79]
	v_cvt_pk_bf16_f32 v157, v214, v215
	v_cvt_pk_bf16_f32 v220, v220, v221
	v_cvt_pk_bf16_f32 v221, v142, v143
	v_cvt_pk_bf16_f32 v222, v136, v137
	v_permlane32_swap_b32_e32 v218, v219
	s_waitcnt lgkmcnt(2)
	v_mfma_f32_32x32x16_bf16 v[64:79], v[248:251], v[104:107], v[64:79]
	ds_read_b128 v[248:251], v182
	ds_read_b128 v[244:247], v211 offset:4096
	v_permlane32_swap_b32_e32 v128, v130
	v_cvt_pk_bf16_f32 v223, v223, v224
	v_permlane32_swap_b32_e32 v220, v222
	v_permlane32_swap_b32_e32 v129, v131
	v_permlane32_swap_b32_e32 v132, v134
	s_waitcnt lgkmcnt(3)
	v_mfma_f32_32x32x16_bf16 v[64:79], v[236:239], v[100:103], v[64:79]
	v_permlane32_swap_b32_e32 v133, v135
	v_permlane32_swap_b32_e32 v154, v156
	v_permlane32_swap_b32_e32 v155, v157
	v_permlane32_swap_b32_e32 v221, v223
	v_lshl_add_u64 v[136:137], s[100:101], 0, v[162:163]
	s_waitcnt lgkmcnt(2)
	v_mfma_f32_32x32x16_bf16 v[64:79], v[240:243], v[96:99], v[64:79]
	ds_read_b128 v[240:243], v182 offset:1024
	ds_read_b128 v[236:239], v210 offset:4096
	v_mul_lo_u32 v138, v137, s40
	v_mul_lo_u32 v139, v136, s41
	v_mad_u64_u32 v[136:137], s[6:7], v136, s40, 0
	v_add3_u32 v137, v137, v139, v138
	v_lshl_add_u64 v[138:139], v[166:167], 0, s[100:101]
	s_waitcnt lgkmcnt(2)
	v_mfma_f32_32x32x16_bf16 v[64:79], v[244:247], v[248:251], v[64:79]
	ds_read_b128 v[248:251], v182 offset:2048
	ds_read_b128 v[244:247], v216 offset:4096
	v_mul_lo_u32 v140, v139, s40
	v_mul_lo_u32 v141, v138, s41
	v_mad_u64_u32 v[138:139], s[6:7], v138, s40, 0
	v_add3_u32 v139, v139, v141, v140
	v_lshlrev_b64 v[146:147], 1, v[136:137]
	s_waitcnt lgkmcnt(2)
	v_mfma_f32_32x32x16_bf16 v[64:79], v[236:239], v[240:243], v[64:79]
	ds_read_b128 v[240:243], v182 offset:3072
	ds_read_b128 v[236:239], v217 offset:4096
	ds_read_b64_tr_b16 v[224:225], v181 offset:0
	ds_read_b64_tr_b16 v[226:227], v181 offset:0x800
	ds_read_b64_tr_b16 v[232:233], v181 offset:0x1000
	ds_read_b64_tr_b16 v[234:235], v181 offset:0x1800
	v_lshlrev_b64 v[148:149], 1, v[138:139]
	v_lshl_add_u64 v[158:159], s[100:101], 0, v[164:165]
	v_lshl_add_u64 v[136:137], v[168:169], 0, v[146:147]
	v_lshl_add_u64 v[140:141], v[168:169], 0, v[148:149]
	v_lshl_add_u64 v[146:147], v[170:171], 0, v[146:147]
	s_waitcnt lgkmcnt(6)
	v_mfma_f32_32x32x16_bf16 v[64:79], v[244:247], v[248:251], v[64:79]
	v_lshl_add_u64 v[150:151], v[170:171], 0, v[148:149]
	v_mad_u64_u32 v[160:161], s[100:101], v158, s3, v[172:173]
	v_mad_i32_i24 v161, v159, s3, v161
	v_max_f32_e32 v250, v81, v81
	v_max_f32_e32 v251, v80, v80
	s_waitcnt lgkmcnt(4)
	v_mfma_f32_32x32x16_bf16 v[64:79], v[236:239], v[240:243], v[64:79]
	ds_read_b64_tr_b16 v[236:237], v181 offset:0x2000
	ds_read_b64_tr_b16 v[238:239], v181 offset:0x2800
	ds_read_b64_tr_b16 v[240:241], v181 offset:0x3000
	ds_read_b64_tr_b16 v[242:243], v181 offset:0x3800
	ds_read_b64_tr_b16 v[212:213], v181 offset:0x200
	ds_read_b64_tr_b16 v[214:215], v181 offset:0xa00
	v_max_f32_e32 v250, v251, v250
	v_max3_f32 v250, v250, v82, v83
	v_max3_f32 v250, v250, v84, v85
	v_max3_f32 v250, v250, v86, v87
	v_max3_f32 v250, v250, v88, v89
	global_load_dwordx4 v[136:139], v[136:137], off
	global_load_dwordx4 v[140:143], v[140:141], off
	global_load_dwordx4 v[146:149], v[146:147], off
	global_load_dwordx4 v[150:153], v[150:151], off
	global_load_dwordx4 v[158:161], v[160:161], off
	s_waitcnt lgkmcnt(8)
	v_mfma_f32_32x32x16_bf16 v[0:15], v[128:131], v[224:227], v[0:15]
	ds_read_b64_tr_b16 v[224:225], v181 offset:0x1200
	ds_read_b64_tr_b16 v[226:227], v181 offset:0x1a00
	v_max3_f32 v250, v250, v90, v91
	v_max3_f32 v250, v250, v92, v93
	v_max3_f32 v250, v250, v94, v95
	v_max3_f32 v250, v250, v64, v65
	v_max3_f32 v250, v250, v66, v67
	s_waitcnt lgkmcnt(8)
	v_mfma_f32_32x32x16_bf16 v[0:15], v[132:135], v[232:235], v[0:15]
	ds_read_b64_tr_b16 v[232:233], v181 offset:0x2200
	ds_read_b64_tr_b16 v[234:235], v181 offset:0x2a00
	v_max3_f32 v250, v250, v68, v69
	v_max3_f32 v250, v250, v70, v71
	v_max3_f32 v250, v250, v72, v73
	v_max3_f32 v250, v250, v74, v75
	v_max3_f32 v250, v250, v76, v77
	s_waitcnt lgkmcnt(8)
	v_mfma_f32_32x32x16_bf16 v[0:15], v[154:157], v[236:239], v[0:15]
	ds_read_b64_tr_b16 v[236:237], v181 offset:0x3200
	ds_read_b64_tr_b16 v[238:239], v181 offset:0x3a00
	v_max3_f32 v250, v250, v78, v79
	v_mov_b32_e32 v251, v250
	s_nop 1
	v_permlane32_swap_b32_e32 v250, v251
	v_max_f32_e32 v251, v251, v251
	v_max_f32_e32 v250, v250, v250
	s_waitcnt lgkmcnt(8)
	v_mfma_f32_32x32x16_bf16 v[0:15], v[220:223], v[240:243], v[0:15]
	ds_read_b64_tr_b16 v[240:241], v181 offset:0x400
	ds_read_b64_tr_b16 v[242:243], v181 offset:0xc00
	v_max_f32_e32 v250, v250, v251
	v_sub_f32_e32 v251, v250, v207
	v_cmp_ge_f32_e32 vcc, s94, v251
	v_max_f32_e32 v251, v207, v207
	v_max_f32_e32 v250, v251, v250
	s_waitcnt lgkmcnt(8)
	v_mfma_f32_32x32x16_bf16 v[48:63], v[128:131], v[212:215], v[48:63]
	ds_read_b64_tr_b16 v[212:213], v181 offset:0x1400
	ds_read_b64_tr_b16 v[214:215], v181 offset:0x1c00
	v_sub_f32_e32 v251, v207, v250
	v_mul_f32_e32 v251, 0x3dd53b94, v251
	v_exp_f32_e32 v251, v251
	s_waitcnt lgkmcnt(8)
	v_mfma_f32_32x32x16_bf16 v[48:63], v[132:135], v[224:227], v[48:63]
	ds_read_b64_tr_b16 v[224:225], v181 offset:0x2400
	ds_read_b64_tr_b16 v[226:227], v181 offset:0x2c00
	s_waitcnt lgkmcnt(8)
	v_mfma_f32_32x32x16_bf16 v[48:63], v[154:157], v[232:235], v[48:63]
	ds_read_b64_tr_b16 v[232:233], v181 offset:0x3400
	ds_read_b64_tr_b16 v[234:235], v181 offset:0x3c00
	s_waitcnt lgkmcnt(8)
	v_mfma_f32_32x32x16_bf16 v[48:63], v[220:223], v[236:239], v[48:63]
	ds_read_b64_tr_b16 v[236:237], v181 offset:0x600
	ds_read_b64_tr_b16 v[238:239], v181 offset:0xe00
	s_waitcnt lgkmcnt(8)
	v_mfma_f32_32x32x16_bf16 v[32:47], v[128:131], v[240:243], v[32:47]
	ds_read_b64_tr_b16 v[240:241], v181 offset:0x1600
	ds_read_b64_tr_b16 v[242:243], v181 offset:0x1e00
	s_waitcnt lgkmcnt(8)
	v_mfma_f32_32x32x16_bf16 v[32:47], v[132:135], v[212:215], v[32:47]
	ds_read_b64_tr_b16 v[212:213], v181 offset:0x2600
	ds_read_b64_tr_b16 v[214:215], v181 offset:0x2e00
	s_waitcnt lgkmcnt(8)
	v_mfma_f32_32x32x16_bf16 v[32:47], v[154:157], v[224:227], v[32:47]
	ds_read_b64_tr_b16 v[224:225], v181 offset:0x3600
	ds_read_b64_tr_b16 v[226:227], v181 offset:0x3e00
	s_waitcnt lgkmcnt(8)
	v_mfma_f32_32x32x16_bf16 v[32:47], v[220:223], v[232:235], v[32:47]
	s_waitcnt lgkmcnt(6)
	v_mfma_f32_32x32x16_bf16 v[16:31], v[128:131], v[236:239], v[16:31]
	s_waitcnt lgkmcnt(4)
	v_mfma_f32_32x32x16_bf16 v[16:31], v[132:135], v[240:243], v[16:31]
	s_waitcnt lgkmcnt(2)
	v_mfma_f32_32x32x16_bf16 v[16:31], v[154:157], v[212:215], v[16:31]
	s_waitcnt lgkmcnt(0)
	v_mfma_f32_32x32x16_bf16 v[16:31], v[220:223], v[224:227], v[16:31]
	s_cmp_eq_u64 vcc, exec
	s_cselect_b64 s[6:7], -1, 0
	s_barrier
	s_waitcnt vmcnt(0)
	v_cndmask_b32_e64 v220, v251, 1.0, s[6:7]
	v_add_u32_e32 v129, 0x10800, v208
	v_cmp_gt_f32_e32 vcc, 1.0, v220
	ds_write_b128 v187, v[146:149] offset:32768
	ds_write_b128 v188, v[150:153] offset:32768
	ds_write_b128 v129, v[158:161]
	ds_write_b128 v185, v[136:139]
	ds_write_b128 v186, v[140:143]
	s_nop 0
	s_nop 0
	s_nop 0
	s_nop 0
	s_nop 0
	s_cbranch_vccz .LBB0_766
	s_and_saveexec_b64 s[0:1], s[4:5]
	ds_write_b32 v183, v220 offset:128
	s_or_b64 exec, exec, s[0:1]
	s_waitcnt lgkmcnt(0)
	v_add_u32_e32 v129, v180, v144
	ds_read_b128 v[130:133], v129 offset:224
	ds_read_b128 v[134:137], v129 offset:192
	ds_read_b128 v[138:141], v129 offset:160
	ds_read_b128 v[146:149], v129 offset:128
	s_waitcnt lgkmcnt(3)
	v_pk_mul_f32 v[12:13], v[12:13], v[130:131]
	s_waitcnt lgkmcnt(2)
	v_pk_mul_f32 v[8:9], v[8:9], v[134:135]
	s_waitcnt lgkmcnt(1)
	v_pk_mul_f32 v[4:5], v[4:5], v[138:139]
	v_pk_mul_f32 v[14:15], v[14:15], v[132:133]
	v_pk_mul_f32 v[10:11], v[10:11], v[136:137]
	v_pk_mul_f32 v[6:7], v[6:7], v[140:141]
	s_waitcnt lgkmcnt(0)
	v_pk_mul_f32 v[2:3], v[2:3], v[148:149]
	v_pk_mul_f32 v[0:1], v[0:1], v[146:147]
	v_pk_mul_f32 v[60:61], v[60:61], v[130:131]
	v_pk_mul_f32 v[56:57], v[56:57], v[134:135]
	v_pk_mul_f32 v[52:53], v[52:53], v[138:139]
	v_pk_mul_f32 v[62:63], v[62:63], v[132:133]
	v_pk_mul_f32 v[58:59], v[58:59], v[136:137]
	v_pk_mul_f32 v[54:55], v[54:55], v[140:141]
	v_pk_mul_f32 v[50:51], v[50:51], v[148:149]
	v_pk_mul_f32 v[48:49], v[48:49], v[146:147]
	v_pk_mul_f32 v[44:45], v[44:45], v[130:131]
	v_pk_mul_f32 v[40:41], v[40:41], v[134:135]
	v_pk_mul_f32 v[36:37], v[36:37], v[138:139]
	v_pk_mul_f32 v[46:47], v[46:47], v[132:133]
	v_pk_mul_f32 v[42:43], v[42:43], v[136:137]
	v_pk_mul_f32 v[38:39], v[38:39], v[140:141]
	v_pk_mul_f32 v[34:35], v[34:35], v[148:149]
	v_pk_mul_f32 v[32:33], v[32:33], v[146:147]
	v_pk_mul_f32 v[28:29], v[28:29], v[130:131]
	v_pk_mul_f32 v[24:25], v[24:25], v[134:135]
	v_pk_mul_f32 v[20:21], v[20:21], v[138:139]
	v_pk_mul_f32 v[30:31], v[30:31], v[132:133]
	v_pk_mul_f32 v[26:27], v[26:27], v[136:137]
	v_pk_mul_f32 v[22:23], v[22:23], v[140:141]
	v_pk_mul_f32 v[18:19], v[18:19], v[148:149]
	v_pk_mul_f32 v[16:17], v[16:17], v[146:147]
.LBB0_766:
	v_cndmask_b32_e64 v207, v250, v207, s[6:7]
	v_mul_f32_e32 v146, 0xbdd53b94, v207
	v_fmamk_f32 v80, v80, 0x3dd53b94, v146
	v_exp_f32_e32 v128, v80
	v_fmamk_f32 v81, v81, 0x3dd53b94, v146
	v_fmamk_f32 v82, v82, 0x3dd53b94, v146
	v_fmamk_f32 v83, v83, 0x3dd53b94, v146
	v_fmamk_f32 v84, v84, 0x3dd53b94, v146
	v_fmamk_f32 v85, v85, 0x3dd53b94, v146
	v_fmamk_f32 v86, v86, 0x3dd53b94, v146
	v_fmamk_f32 v87, v87, 0x3dd53b94, v146
	v_fmamk_f32 v88, v88, 0x3dd53b94, v146
	v_fmamk_f32 v89, v89, 0x3dd53b94, v146
	v_fmamk_f32 v90, v90, 0x3dd53b94, v146
	v_fmamk_f32 v91, v91, 0x3dd53b94, v146
	v_fmamk_f32 v92, v92, 0x3dd53b94, v146
	v_fmamk_f32 v93, v93, 0x3dd53b94, v146
	v_fmamk_f32 v94, v94, 0x3dd53b94, v146
	v_fmamk_f32 v95, v95, 0x3dd53b94, v146
	v_fmamk_f32 v155, v64, 0x3dd53b94, v146
	v_fmamk_f32 v156, v65, 0x3dd53b94, v146
	v_fmamk_f32 v157, v66, 0x3dd53b94, v146
	v_fmamk_f32 v158, v67, 0x3dd53b94, v146
	v_fmamk_f32 v159, v68, 0x3dd53b94, v146
	v_fmamk_f32 v148, v69, 0x3dd53b94, v146
	v_fmamk_f32 v149, v70, 0x3dd53b94, v146
	v_fmamk_f32 v150, v71, 0x3dd53b94, v146
	v_fmamk_f32 v151, v72, 0x3dd53b94, v146
	v_fmamk_f32 v152, v73, 0x3dd53b94, v146
	v_fmamk_f32 v153, v74, 0x3dd53b94, v146
	v_fmamk_f32 v154, v75, 0x3dd53b94, v146
	v_fmamk_f32 v147, v76, 0x3dd53b94, v146
	v_exp_f32_e32 v143, v81
	v_exp_f32_e32 v129, v82
	v_exp_f32_e32 v142, v83
	v_exp_f32_e32 v130, v84
	v_exp_f32_e32 v141, v85
	v_exp_f32_e32 v131, v86
	v_exp_f32_e32 v140, v87
	v_exp_f32_e32 v132, v88
	v_exp_f32_e32 v139, v89
	v_exp_f32_e32 v133, v90
	v_exp_f32_e32 v138, v91
	v_exp_f32_e32 v134, v92
	v_exp_f32_e32 v137, v93
	v_exp_f32_e32 v135, v94
	v_exp_f32_e32 v136, v95
	v_fmamk_f32 v160, v77, 0x3dd53b94, v146
	v_fmamk_f32 v161, v78, 0x3dd53b94, v146
	v_fmac_f32_e32 v146, 0x3dd53b94, v79
	s_waitcnt lgkmcnt(2)
	s_barrier
	ds_read_b128 v[64:67], v189 offset:32768
	ds_read_b128 v[240:243], v191 offset:32768
	ds_read_b128 v[244:247], v193 offset:32768
	ds_read_b128 v[248:251], v195 offset:32768
	s_cmp_lt_u32 s9, 2
	s_cselect_b32 s100, s46, s68
	s_add_i32 s100, s100, s8
	s_add_i32 s100, s100, 64
	s_ashr_i32 s101, s100, 31
	s_waitcnt lgkmcnt(3)
	v_mfma_f32_32x32x16_bf16 v[80:95], v[64:67], v[124:127], 0
	v_exp_f32_e32 v212, v154
	v_add_f32_e32 v154, 0, v128
	v_add_f32_e32 v154, v143, v154
	v_add_f32_e32 v154, v129, v154
	s_waitcnt lgkmcnt(2)
	v_mfma_f32_32x32x16_bf16 v[80:95], v[240:243], v[120:123], v[80:95]
	ds_read_b128 v[240:243], v196 offset:32768
	v_add_f32_e32 v154, v142, v154
	v_add_f32_e32 v154, v130, v154
	v_add_f32_e32 v154, v141, v154
	v_add_f32_e32 v154, v131, v154
	v_add_f32_e32 v154, v140, v154
	s_waitcnt lgkmcnt(2)
	v_mfma_f32_32x32x16_bf16 v[80:95], v[244:247], v[116:119], v[80:95]
	ds_read_b128 v[244:247], v194 offset:32768
	v_add_f32_e32 v154, v132, v154
	v_add_f32_e32 v154, v139, v154
	v_add_f32_e32 v154, v133, v154
	v_add_f32_e32 v154, v138, v154
	v_add_f32_e32 v154, v134, v154
	s_waitcnt lgkmcnt(2)
	v_mfma_f32_32x32x16_bf16 v[80:95], v[248:251], v[112:115], v[80:95]
	ds_read_b128 v[248:251], v192 offset:32768
	v_exp_f32_e32 v155, v155
	v_exp_f32_e32 v156, v156
	v_add_f32_e32 v154, v137, v154
	s_waitcnt lgkmcnt(2)
	v_mfma_f32_32x32x16_bf16 v[80:95], v[240:243], v[108:111], v[80:95]
	ds_read_b128 v[240:243], v190 offset:32768
	v_exp_f32_e32 v157, v157
	v_add_f32_e32 v154, v135, v154
	v_exp_f32_e32 v158, v158
	s_waitcnt lgkmcnt(2)
	v_mfma_f32_32x32x16_bf16 v[80:95], v[244:247], v[104:107], v[80:95]
	ds_read_b128 v[244:247], v199
	v_add_f32_e32 v154, v136, v154
	v_exp_f32_e32 v159, v159
	v_add_f32_e32 v154, v155, v154
	v_add_f32_e32 v154, v156, v154
	s_waitcnt lgkmcnt(2)
	v_mfma_f32_32x32x16_bf16 v[80:95], v[248:251], v[100:103], v[80:95]
	ds_read_b128 v[248:251], v182
	v_exp_f32_e32 v148, v148
	v_exp_f32_e32 v149, v149
	v_add_f32_e32 v154, v157, v154
	s_waitcnt lgkmcnt(2)
	v_mfma_f32_32x32x16_bf16 v[80:95], v[240:243], v[96:99], v[80:95]
	ds_read_b128 v[240:243], v201
	v_exp_f32_e32 v150, v150
	v_add_f32_e32 v154, v158, v154
	v_exp_f32_e32 v151, v151
	s_waitcnt lgkmcnt(1)
	v_mfma_f32_32x32x16_bf16 v[80:95], v[244:247], v[248:251], v[80:95]
	ds_read_b128 v[244:247], v182 offset:1024
	ds_read_b128 v[248:251], v203
	v_add_f32_e32 v154, v159, v154
	v_exp_f32_e32 v152, v152
	v_add_f32_e32 v154, v148, v154
	v_add_f32_e32 v154, v149, v154
	s_waitcnt lgkmcnt(1)
	v_mfma_f32_32x32x16_bf16 v[80:95], v[240:243], v[244:247], v[80:95]
	ds_read_b128 v[240:243], v182 offset:2048
	ds_read_b128 v[244:247], v205
	v_exp_f32_e32 v153, v153
	v_add_f32_e32 v154, v150, v154
	v_exp_f32_e32 v147, v147
	s_waitcnt lgkmcnt(1)
	v_mfma_f32_32x32x16_bf16 v[80:95], v[248:251], v[240:243], v[80:95]
	ds_read_b128 v[248:251], v182 offset:3072
	ds_read_b128 v[68:71], v189 offset:40960
	ds_read_b128 v[240:243], v191 offset:40960
	v_add_f32_e32 v154, v151, v154
	v_exp_f32_e32 v160, v160
	v_add_f32_e32 v154, v152, v154
	v_add_f32_e32 v154, v153, v154
	s_waitcnt lgkmcnt(2)
	v_mfma_f32_32x32x16_bf16 v[80:95], v[244:247], v[248:251], v[80:95]
	ds_read_b128 v[244:247], v193 offset:40960
	ds_read_b128 v[248:251], v195 offset:40960
	v_exp_f32_e32 v161, v161
	v_exp_f32_e32 v146, v146
	v_add_f32_e32 v154, v212, v154
	s_waitcnt lgkmcnt(3)
	v_mfma_f32_32x32x16_bf16 v[64:79], v[68:71], v[124:127], 0
	v_add_f32_e32 v154, v147, v154
	v_add_f32_e32 v154, v160, v154
	v_add_f32_e32 v154, v161, v154
	v_cvt_pk_bf16_f32 v128, v128, v143
	v_cvt_pk_bf16_f32 v129, v129, v142
	s_waitcnt lgkmcnt(2)
	v_mfma_f32_32x32x16_bf16 v[64:79], v[240:243], v[120:123], v[64:79]
	ds_read_b128 v[240:243], v196 offset:40960
	v_cvt_pk_bf16_f32 v130, v130, v141
	v_cvt_pk_bf16_f32 v131, v131, v140
	v_cvt_pk_bf16_f32 v132, v132, v139
	v_cvt_pk_bf16_f32 v133, v133, v138
	v_add_f32_e32 v222, v146, v154
	s_waitcnt lgkmcnt(2)
	v_mfma_f32_32x32x16_bf16 v[64:79], v[244:247], v[116:119], v[64:79]
	ds_read_b128 v[244:247], v194 offset:40960
	v_mov_b32_e32 v223, v222
	s_nop 1
	v_permlane32_swap_b32_e32 v222, v223
	v_permlane32_swap_b32_e32 v128, v130
	v_cvt_pk_bf16_f32 v134, v134, v137
	v_cvt_pk_bf16_f32 v135, v135, v136
	s_waitcnt lgkmcnt(2)
	v_mfma_f32_32x32x16_bf16 v[64:79], v[248:251], v[112:115], v[64:79]
	ds_read_b128 v[248:251], v192 offset:40960
	v_cvt_pk_bf16_f32 v154, v155, v156
	v_cvt_pk_bf16_f32 v155, v157, v158
	v_cvt_pk_bf16_f32 v156, v159, v148
	v_cvt_pk_bf16_f32 v157, v149, v150
	v_cvt_pk_bf16_f32 v224, v151, v152
	s_waitcnt lgkmcnt(2)
	v_mfma_f32_32x32x16_bf16 v[64:79], v[240:243], v[108:111], v[64:79]
	ds_read_b128 v[240:243], v190 offset:40960
	v_cvt_pk_bf16_f32 v225, v153, v212
	v_cvt_pk_bf16_f32 v226, v147, v160
	v_cvt_pk_bf16_f32 v227, v161, v146
	v_permlane32_swap_b32_e32 v129, v131
	v_permlane32_swap_b32_e32 v132, v134
	s_waitcnt lgkmcnt(2)
	v_mfma_f32_32x32x16_bf16 v[64:79], v[244:247], v[104:107], v[64:79]
	v_permlane32_swap_b32_e32 v133, v135
	v_permlane32_swap_b32_e32 v154, v156
	v_permlane32_swap_b32_e32 v155, v157
	v_permlane32_swap_b32_e32 v224, v226
	v_permlane32_swap_b32_e32 v225, v227
	s_waitcnt lgkmcnt(1)
	v_mfma_f32_32x32x16_bf16 v[64:79], v[248:251], v[100:103], v[64:79]
	ds_read_b128 v[248:251], v182
	ds_read_b128 v[244:247], v199 offset:4096
	v_lshl_add_u64 v[136:137], s[100:101], 0, v[162:163]
	v_mul_lo_u32 v138, v137, s40
	v_mul_lo_u32 v139, v136, s41
	v_mad_u64_u32 v[136:137], s[6:7], v136, s40, 0
	v_add3_u32 v137, v137, v139, v138
	s_waitcnt lgkmcnt(2)
	v_mfma_f32_32x32x16_bf16 v[64:79], v[240:243], v[96:99], v[64:79]
	v_lshl_add_u64 v[138:139], v[166:167], 0, s[100:101]
	v_mul_lo_u32 v140, v139, s40
	v_mul_lo_u32 v141, v138, s41
	v_mad_u64_u32 v[138:139], s[6:7], v138, s40, 0
	v_add3_u32 v139, v139, v141, v140
	s_waitcnt lgkmcnt(0)
	v_mfma_f32_32x32x16_bf16 v[64:79], v[244:247], v[248:251], v[64:79]
	ds_read_b128 v[244:247], v182 offset:1024
	ds_read_b128 v[240:243], v201 offset:4096
	v_lshlrev_b64 v[146:147], 1, v[136:137]
	v_lshlrev_b64 v[148:149], 1, v[138:139]
	v_lshl_add_u64 v[158:159], s[100:101], 0, v[164:165]
	v_lshl_add_u64 v[136:137], v[168:169], 0, v[146:147]
	v_lshl_add_u64 v[140:141], v[168:169], 0, v[148:149]
	s_waitcnt lgkmcnt(0)
	v_mfma_f32_32x32x16_bf16 v[64:79], v[240:243], v[244:247], v[64:79]
	ds_read_b128 v[240:243], v182 offset:2048
	ds_read_b128 v[248:251], v203 offset:4096
	v_lshl_add_u64 v[146:147], v[170:171], 0, v[146:147]
	v_lshl_add_u64 v[150:151], v[170:171], 0, v[148:149]
	v_mad_u64_u32 v[160:161], s[100:101], v158, s3, v[172:173]
	v_mad_i32_i24 v161, v159, s3, v161
	s_waitcnt lgkmcnt(0)
	v_mfma_f32_32x32x16_bf16 v[64:79], v[248:251], v[240:243], v[64:79]
	ds_read_b128 v[248:251], v182 offset:3072
	ds_read_b128 v[244:247], v205 offset:4096
	ds_read_b64_tr_b16 v[232:233], v184 offset:0
	ds_read_b64_tr_b16 v[234:235], v184 offset:0x800
	ds_read_b64_tr_b16 v[236:237], v184 offset:0x1000
	ds_read_b64_tr_b16 v[238:239], v184 offset:0x1800
	ds_read_b64_tr_b16 v[240:241], v184 offset:0x2000
	ds_read_b64_tr_b16 v[242:243], v184 offset:0x2800
	s_waitcnt lgkmcnt(6)
	v_mfma_f32_32x32x16_bf16 v[64:79], v[244:247], v[248:251], v[64:79]
	ds_read_b64_tr_b16 v[244:245], v184 offset:0x3000
	ds_read_b64_tr_b16 v[246:247], v184 offset:0x3800
	v_max_f32_e32 v250, v81, v81
	v_max_f32_e32 v251, v80, v80
	v_max_f32_e32 v250, v251, v250
	v_max3_f32 v250, v250, v82, v83
	v_max3_f32 v250, v250, v84, v85
	global_load_dwordx4 v[136:139], v[136:137], off
	global_load_dwordx4 v[140:143], v[140:141], off
	global_load_dwordx4 v[146:149], v[146:147], off
	global_load_dwordx4 v[150:153], v[150:151], off
	global_load_dwordx4 v[158:161], v[160:161], off
	s_waitcnt lgkmcnt(6)
	v_mfma_f32_32x32x16_bf16 v[0:15], v[128:131], v[232:235], v[0:15]
	ds_read_b64_tr_b16 v[232:233], v184 offset:0x200
	ds_read_b64_tr_b16 v[234:235], v184 offset:0xa00
	v_max3_f32 v250, v250, v86, v87
	v_max3_f32 v250, v250, v88, v89
	v_max3_f32 v250, v250, v90, v91
	v_max3_f32 v250, v250, v92, v93
	v_max3_f32 v250, v250, v94, v95
	s_waitcnt lgkmcnt(6)
	v_mfma_f32_32x32x16_bf16 v[0:15], v[132:135], v[236:239], v[0:15]
	ds_read_b64_tr_b16 v[236:237], v184 offset:0x1200
	ds_read_b64_tr_b16 v[238:239], v184 offset:0x1a00
	v_max3_f32 v250, v250, v64, v65
	v_max3_f32 v250, v250, v66, v67
	v_max3_f32 v250, v250, v68, v69
	v_max3_f32 v250, v250, v70, v71
	v_max3_f32 v250, v250, v72, v73
	s_waitcnt lgkmcnt(6)
	v_mfma_f32_32x32x16_bf16 v[0:15], v[154:157], v[240:243], v[0:15]
	ds_read_b64_tr_b16 v[240:241], v184 offset:0x2200
	ds_read_b64_tr_b16 v[242:243], v184 offset:0x2a00
	v_max3_f32 v250, v250, v74, v75
	v_max3_f32 v250, v250, v76, v77
	v_max3_f32 v250, v250, v78, v79
	v_mov_b32_e32 v251, v250
	s_nop 1
	v_permlane32_swap_b32_e32 v250, v251
	s_waitcnt lgkmcnt(6)
	v_mfma_f32_32x32x16_bf16 v[0:15], v[224:227], v[244:247], v[0:15]
	ds_read_b64_tr_b16 v[244:245], v184 offset:0x3200
	ds_read_b64_tr_b16 v[246:247], v184 offset:0x3a00
	v_max_f32_e32 v251, v251, v251
	v_max_f32_e32 v250, v250, v250
	v_max_f32_e32 v250, v250, v251
	v_sub_f32_e32 v251, v250, v207
	v_cmp_ge_f32_e32 vcc, s94, v251
	s_waitcnt lgkmcnt(6)
	v_mfma_f32_32x32x16_bf16 v[48:63], v[128:131], v[232:235], v[48:63]
	ds_read_b64_tr_b16 v[232:233], v184 offset:0x400
	ds_read_b64_tr_b16 v[234:235], v184 offset:0xc00
	v_max_f32_e32 v251, v207, v207
	v_max_f32_e32 v250, v251, v250
	v_sub_f32_e32 v251, v207, v250
	v_mul_f32_e32 v251, 0x3dd53b94, v251
	s_waitcnt lgkmcnt(6)
	v_mfma_f32_32x32x16_bf16 v[48:63], v[132:135], v[236:239], v[48:63]
	ds_read_b64_tr_b16 v[236:237], v184 offset:0x1400
	ds_read_b64_tr_b16 v[238:239], v184 offset:0x1c00
	v_exp_f32_e32 v251, v251
	s_waitcnt lgkmcnt(6)
	v_mfma_f32_32x32x16_bf16 v[48:63], v[154:157], v[240:243], v[48:63]
	ds_read_b64_tr_b16 v[240:241], v184 offset:0x2400
	ds_read_b64_tr_b16 v[242:243], v184 offset:0x2c00
	s_waitcnt lgkmcnt(6)
	v_mfma_f32_32x32x16_bf16 v[48:63], v[224:227], v[244:247], v[48:63]
	ds_read_b64_tr_b16 v[244:245], v184 offset:0x3400
	ds_read_b64_tr_b16 v[246:247], v184 offset:0x3c00
	s_waitcnt lgkmcnt(6)
	v_mfma_f32_32x32x16_bf16 v[32:47], v[128:131], v[232:235], v[32:47]
	ds_read_b64_tr_b16 v[232:233], v184 offset:0x600
	ds_read_b64_tr_b16 v[234:235], v184 offset:0xe00
	s_waitcnt lgkmcnt(6)
	v_mfma_f32_32x32x16_bf16 v[32:47], v[132:135], v[236:239], v[32:47]
	ds_read_b64_tr_b16 v[236:237], v184 offset:0x1600
	ds_read_b64_tr_b16 v[238:239], v184 offset:0x1e00
	s_waitcnt lgkmcnt(6)
	v_mfma_f32_32x32x16_bf16 v[32:47], v[154:157], v[240:243], v[32:47]
	ds_read_b64_tr_b16 v[240:241], v184 offset:0x2600
	ds_read_b64_tr_b16 v[242:243], v184 offset:0x2e00
	s_waitcnt lgkmcnt(6)
	v_mfma_f32_32x32x16_bf16 v[32:47], v[224:227], v[244:247], v[32:47]
	ds_read_b64_tr_b16 v[244:245], v184 offset:0x3600
	ds_read_b64_tr_b16 v[246:247], v184 offset:0x3e00
	s_waitcnt lgkmcnt(6)
	v_mfma_f32_32x32x16_bf16 v[16:31], v[128:131], v[232:235], v[16:31]
	s_waitcnt lgkmcnt(4)
	v_mfma_f32_32x32x16_bf16 v[16:31], v[132:135], v[236:239], v[16:31]
	s_waitcnt lgkmcnt(2)
	v_mfma_f32_32x32x16_bf16 v[16:31], v[154:157], v[240:243], v[16:31]
	s_waitcnt lgkmcnt(0)
	v_mfma_f32_32x32x16_bf16 v[16:31], v[224:227], v[244:247], v[16:31]
	s_cmp_eq_u64 vcc, exec
	s_cselect_b64 s[6:7], -1, 0
	s_barrier
	s_waitcnt vmcnt(0)
	v_cndmask_b32_e64 v221, v251, 1.0, s[6:7]
	v_cmp_gt_f32_e32 vcc, 1.0, v221
	ds_write_b128 v187, v[146:149] offset:49152
	ds_write_b128 v188, v[150:153] offset:49152
	ds_write_b128 v209, v[158:161]
	ds_write_b128 v185, v[136:139] offset:16384
	ds_write_b128 v186, v[140:143] offset:16384
	s_nop 0
	s_nop 0
	s_nop 0
	s_nop 0
	s_nop 0
	s_cbranch_vccz .LBB0_770
	s_and_saveexec_b64 s[0:1], s[4:5]
	ds_write_b32 v183, v221 offset:128
	s_or_b64 exec, exec, s[0:1]
	s_waitcnt lgkmcnt(0)
	v_add_u32_e32 v129, v180, v144
	ds_read_b128 v[130:133], v129 offset:224
	ds_read_b128 v[134:137], v129 offset:192
	ds_read_b128 v[138:141], v129 offset:160
	ds_read_b128 v[146:149], v129 offset:128
	s_waitcnt lgkmcnt(3)
	v_pk_mul_f32 v[12:13], v[12:13], v[130:131]
	s_waitcnt lgkmcnt(2)
	v_pk_mul_f32 v[8:9], v[8:9], v[134:135]
	s_waitcnt lgkmcnt(1)
	v_pk_mul_f32 v[4:5], v[4:5], v[138:139]
	v_pk_mul_f32 v[14:15], v[14:15], v[132:133]
	v_pk_mul_f32 v[10:11], v[10:11], v[136:137]
	v_pk_mul_f32 v[6:7], v[6:7], v[140:141]
	s_waitcnt lgkmcnt(0)
	v_pk_mul_f32 v[2:3], v[2:3], v[148:149]
	v_pk_mul_f32 v[0:1], v[0:1], v[146:147]
	v_pk_mul_f32 v[60:61], v[60:61], v[130:131]
	v_pk_mul_f32 v[56:57], v[56:57], v[134:135]
	v_pk_mul_f32 v[52:53], v[52:53], v[138:139]
	v_pk_mul_f32 v[62:63], v[62:63], v[132:133]
	v_pk_mul_f32 v[58:59], v[58:59], v[136:137]
	v_pk_mul_f32 v[54:55], v[54:55], v[140:141]
	v_pk_mul_f32 v[50:51], v[50:51], v[148:149]
	v_pk_mul_f32 v[48:49], v[48:49], v[146:147]
	v_pk_mul_f32 v[44:45], v[44:45], v[130:131]
	v_pk_mul_f32 v[40:41], v[40:41], v[134:135]
	v_pk_mul_f32 v[36:37], v[36:37], v[138:139]
	v_pk_mul_f32 v[46:47], v[46:47], v[132:133]
	v_pk_mul_f32 v[42:43], v[42:43], v[136:137]
	v_pk_mul_f32 v[38:39], v[38:39], v[140:141]
	v_pk_mul_f32 v[34:35], v[34:35], v[148:149]
	v_pk_mul_f32 v[32:33], v[32:33], v[146:147]
	v_pk_mul_f32 v[28:29], v[28:29], v[130:131]
	v_pk_mul_f32 v[24:25], v[24:25], v[134:135]
	v_pk_mul_f32 v[20:21], v[20:21], v[138:139]
	v_pk_mul_f32 v[30:31], v[30:31], v[132:133]
	v_pk_mul_f32 v[26:27], v[26:27], v[136:137]
	v_pk_mul_f32 v[22:23], v[22:23], v[140:141]
	v_pk_mul_f32 v[18:19], v[18:19], v[148:149]
	v_pk_mul_f32 v[16:17], v[16:17], v[146:147]
